# grid barrier: reciprocal part of the two leader-test divisions computed in the shadow of the arrive and TOP atomics
# baseline (speedup 1.0000x reference)
.LBB0_571:
	s_or_b64 exec, exec, s[2:3]
	v_cvt_f32_u32_e32 v5, v3
	v_sub_u32_e32 v6, 0, v3
	v_rcp_iflag_f32_e32 v5, v5
	s_nop 0
	v_mul_f32_e32 v5, 0x4f7ffffe, v5
	v_cvt_u32_f32_e32 v5, v5
	v_mul_lo_u32 v6, v6, v5
	v_mul_hi_u32 v6, v5, v6
	v_add_u32_e32 v5, v5, v6
	s_waitcnt vmcnt(0)
	v_readfirstlane_b32 s2, v4
	s_nop 1
	v_add_u32_e32 v6, s2, v0
	v_mul_hi_u32 v0, v6, v5
	v_mul_lo_u32 v4, v0, v3
	v_sub_u32_e32 v4, v6, v4
	v_add_u32_e32 v5, 1, v0
	v_cmp_ge_u32_e32 vcc, v4, v3
	s_nop 1
	v_cndmask_b32_e32 v0, v0, v5, vcc
	v_sub_u32_e32 v5, v4, v3
	v_cndmask_b32_e32 v4, v4, v5, vcc
	v_add_u32_e32 v5, 1, v0
	v_cmp_ge_u32_e32 vcc, v4, v3
	v_add_u32_e32 v4, 1, v6
	s_nop 0
	v_cndmask_b32_e32 v0, v0, v5, vcc
	v_mul_lo_u32 v5, v3, v0
	v_add_u32_e32 v3, v5, v3
	v_cmp_ne_u32_e32 vcc, v4, v3
	s_and_saveexec_b64 s[2:3], vcc
	s_xor_b64 s[2:3], exec, s[2:3]
	s_cbranch_execz .LBB0_585
	v_readlane_b32 s4, v215, 22
	v_readlane_b32 s5, v215, 23
	s_waitcnt lgkmcnt(0)
	s_nop 3
	buffer_inv sc1
	global_load_dword v2, v1, s[4:5] sc1
	s_waitcnt vmcnt(0)
	v_cmp_eq_u32_e32 vcc, v2, v0
	s_and_saveexec_b64 s[4:5], vcc
	s_cbranch_execz .LBB0_584
	s_mov_b32 s16, 1
	s_mov_b64 s[6:7], 0
	s_branch .LBB0_575

.LBB0_588:
	s_or_b64 exec, exec, s[4:5]
	buffer_inv sc1
	v_sub_u32_e32 v4, 0, v2
	v_cvt_f32_u32_e32 v5, v2
	v_rcp_iflag_f32_e32 v5, v5
	s_nop 0
	v_mul_f32_e32 v5, 0x4f7ffffe, v5
	v_cvt_u32_f32_e32 v5, v5
	v_mul_lo_u32 v4, v4, v5
	v_mul_hi_u32 v4, v5, v4
	v_add_u32_e32 v5, v5, v4
	s_waitcnt vmcnt(0)
	v_readfirstlane_b32 s2, v3
	s_mov_b64 s[4:5], -1
	s_nop 0
	v_add_u32_e32 v3, s2, v0
	v_readlane_b32 s2, v215, 26
	v_readlane_b32 s3, v215, 27
	v_mul_hi_u32 v0, v3, v5
	v_mul_lo_u32 v4, v0, v2
	v_sub_u32_e32 v4, v3, v4
	v_cmp_ge_u32_e32 vcc, v4, v2
	v_add_u32_e32 v5, 1, v0
	v_add_u32_e32 v3, 1, v3
	v_cndmask_b32_e32 v0, v0, v5, vcc
	v_sub_u32_e32 v5, v4, v2
	v_cndmask_b32_e32 v4, v4, v5, vcc
	v_cmp_ge_u32_e32 vcc, v4, v2
	v_add_u32_e32 v4, 1, v0
	s_nop 0
	v_cndmask_b32_e32 v0, v0, v4, vcc
	v_mul_lo_u32 v4, v2, v0
	v_add_u32_e32 v2, v4, v2
	v_cmp_ne_u32_e32 vcc, v3, v2
	v_mov_b64_e32 v[2:3], s[2:3]
	s_mov_b32 s16, 0
	s_and_saveexec_b64 s[2:3], vcc
	s_cbranch_execz .LBB0_600
	s_mov_b32 s16, 1
	v_readlane_b32 s4, v215, 26
	v_readlane_b32 s5, v215, 27
	s_mov_b64 s[6:7], 0
	s_nop 3
	global_load_dword v2, v1, s[4:5] sc1
	s_waitcnt vmcnt(0)
	v_cmp_eq_u32_e32 vcc, v2, v0
	s_and_saveexec_b64 s[4:5], vcc
	s_cbranch_execz .LBB0_599
	s_mov_b32 s16, 1
	s_branch .LBB0_592
